# attention: one static s_setprio 1 for waves 4-7 during the attention part of phase 3 (docs 7.4), reset before the chunk gate
# baseline (speedup 1.0000x reference)
.Lp3_attn:
	v_readfirstlane_b32 s84, v208
	s_nop 3
	s_lshr_b32 s84, s84, 6
	s_cmp_ge_u32 s84, 4
	s_cbranch_scc0 .Lp3_prio_done
	s_setprio 1

.LBB0_449:
	s_setprio 0
	v_readlane_b32 s48, v255, 6
	s_cmpk_gt_i32 s97, 0xff
	v_readlane_b32 s49, v255, 7
	s_cbranch_scc1 .LBB0_458
	s_cmp_eq_u32 s98, 2
	s_cbranch_scc1 .LBB0_458
	v_mbcnt_hi_u32_b32 v100, -1, v246
	s_add_u32 s2, s90, 0x19000020
	v_and_b32_e32 v0, 64, v100
	s_addc_u32 s3, s91, 0
	s_lshl_b32 s1, s97, 7
	s_lshl_b32 s7, s48, 7
	v_xor_b32_e32 v101, 1, v100
	v_add_u32_e32 v102, 64, v0
	v_xor_b32_e32 v103, 2, v100
	s_mov_b32 s6, 0x3a800000
	s_mov_b32 s28, 0x800000
	v_mov_b32_e32 v33, 0
	s_movk_i32 s29, 0xffe0
	s_movk_i32 s30, 0x110
	s_mov_b64 s[8:9], 0x6c00800
	s_mov_b64 s[12:13], 0x19000000
	s_mov_b64 s[14:15], 0x12c00000
	s_mov_b64 s[16:17], 0x100
	s_mov_b64 s[18:19], 0x8000
	s_mov_b32 s31, s97
